# P1 and P8 tile transitions: first k-iteration of every later tile runs from a peeled copy whose first two counted waits let the previous epilogue's 16 stores stay in flight
# baseline (speedup 1.0000x reference)
.LBB0_74:
	s_add_u32 s40, s40, 0x40080
	s_addc_u32 s41, s41, 0
	s_add_u32 s17, s50, 0x100
	v_mov_b32_e32 v0, 0
	s_addc_u32 s19, s51, 0
	s_mov_b32 s83, -2
	v_mov_b32_e32 v1, v0
	v_mov_b32_e32 v2, v0
	v_mov_b32_e32 v3, v0
	v_mov_b32_e32 v4, v0
	v_mov_b32_e32 v5, v0
	v_mov_b32_e32 v6, v0
	v_mov_b32_e32 v7, v0
	v_mov_b32_e32 v8, v0
	v_mov_b32_e32 v9, v0
	v_mov_b32_e32 v10, v0
	v_mov_b32_e32 v11, v0
	v_mov_b32_e32 v16, v0
	v_mov_b32_e32 v17, v0
	v_mov_b32_e32 v18, v0
	v_mov_b32_e32 v19, v0
	v_mov_b32_e32 v24, v0
	v_mov_b32_e32 v25, v0
	v_mov_b32_e32 v26, v0
	v_mov_b32_e32 v27, v0
	v_mov_b32_e32 v32, v0
	v_mov_b32_e32 v33, v0
	v_mov_b32_e32 v34, v0
	v_mov_b32_e32 v35, v0
	v_mov_b32_e32 v40, v0
	v_mov_b32_e32 v41, v0
	v_mov_b32_e32 v42, v0
	v_mov_b32_e32 v43, v0
	v_mov_b32_e32 v48, v0
	v_mov_b32_e32 v49, v0
	v_mov_b32_e32 v50, v0
	v_mov_b32_e32 v51, v0
	v_mov_b32_e32 v12, v0
	v_mov_b32_e32 v13, v0
	v_mov_b32_e32 v14, v0
	v_mov_b32_e32 v15, v0
	v_mov_b32_e32 v20, v0
	v_mov_b32_e32 v21, v0
	v_mov_b32_e32 v22, v0
	v_mov_b32_e32 v23, v0
	v_mov_b32_e32 v28, v0
	v_mov_b32_e32 v29, v0
	v_mov_b32_e32 v30, v0
	v_mov_b32_e32 v31, v0
	v_mov_b32_e32 v36, v0
	v_mov_b32_e32 v37, v0
	v_mov_b32_e32 v38, v0
	v_mov_b32_e32 v39, v0
	v_mov_b32_e32 v44, v0
	v_mov_b32_e32 v45, v0
	v_mov_b32_e32 v46, v0
	v_mov_b32_e32 v47, v0
	v_mov_b32_e32 v52, v0
	v_mov_b32_e32 v53, v0
	v_mov_b32_e32 v54, v0
	v_mov_b32_e32 v55, v0
	v_mov_b32_e32 v56, v0
	v_mov_b32_e32 v57, v0
	v_mov_b32_e32 v58, v0
	v_mov_b32_e32 v59, v0
	v_mov_b32_e32 v60, v0
	v_mov_b32_e32 v61, v0
	v_mov_b32_e32 v62, v0
	v_mov_b32_e32 v63, v0
	v_mov_b32_e32 v64, v0
	v_mov_b32_e32 v65, v0
	v_mov_b32_e32 v66, v0
	v_mov_b32_e32 v67, v0
	v_mov_b32_e32 v68, v0
	v_mov_b32_e32 v69, v0
	v_mov_b32_e32 v70, v0
	v_mov_b32_e32 v71, v0
	v_mov_b32_e32 v72, v0
	v_mov_b32_e32 v73, v0
	v_mov_b32_e32 v74, v0
	v_mov_b32_e32 v75, v0
	v_mov_b32_e32 v80, v0
	v_mov_b32_e32 v81, v0
	v_mov_b32_e32 v82, v0
	v_mov_b32_e32 v83, v0
	v_mov_b32_e32 v88, v0
	v_mov_b32_e32 v89, v0
	v_mov_b32_e32 v90, v0
	v_mov_b32_e32 v91, v0
	v_mov_b32_e32 v96, v0
	v_mov_b32_e32 v97, v0
	v_mov_b32_e32 v98, v0
	v_mov_b32_e32 v99, v0
	v_mov_b32_e32 v104, v0
	v_mov_b32_e32 v105, v0
	v_mov_b32_e32 v106, v0
	v_mov_b32_e32 v107, v0
	v_mov_b32_e32 v112, v0
	v_mov_b32_e32 v113, v0
	v_mov_b32_e32 v114, v0
	v_mov_b32_e32 v115, v0
	v_mov_b32_e32 v76, v0
	v_mov_b32_e32 v77, v0
	v_mov_b32_e32 v78, v0
	v_mov_b32_e32 v79, v0
	v_mov_b32_e32 v84, v0
	v_mov_b32_e32 v85, v0
	v_mov_b32_e32 v86, v0
	v_mov_b32_e32 v87, v0
	v_mov_b32_e32 v92, v0
	v_mov_b32_e32 v93, v0
	v_mov_b32_e32 v94, v0
	v_mov_b32_e32 v95, v0
	v_mov_b32_e32 v100, v0
	v_mov_b32_e32 v101, v0
	v_mov_b32_e32 v102, v0
	v_mov_b32_e32 v103, v0
	v_mov_b32_e32 v108, v0
	v_mov_b32_e32 v109, v0
	v_mov_b32_e32 v110, v0
	v_mov_b32_e32 v111, v0
	v_mov_b32_e32 v116, v0
	v_mov_b32_e32 v117, v0
	v_mov_b32_e32 v118, v0
	v_mov_b32_e32 v119, v0
	v_mov_b32_e32 v120, v0
	v_mov_b32_e32 v121, v0
	v_mov_b32_e32 v122, v0
	v_mov_b32_e32 v123, v0
	v_mov_b32_e32 v124, v0
	v_mov_b32_e32 v125, v0
	v_mov_b32_e32 v126, v0
	v_mov_b32_e32 v127, v0
	s_cmp_eq_u32 s75, 1
	s_cbranch_scc1 .LBB0_75
	ds_read_b128 v[144:147], v151
	ds_read_b128 v[154:157], v151 offset:1024
	ds_read_b128 v[162:165], v151 offset:2048
	ds_read_b128 v[166:169], v151 offset:3072
	ds_read_b128 v[170:173], v152
	ds_read_b128 v[174:177], v152 offset:1024
	ds_read_b128 v[182:185], v152 offset:2048
	ds_read_b128 v[186:189], v152 offset:3072
	s_add_u32 s50, s40, 0xfffc0080
	s_addc_u32 s51, s41, -1
	s_cmp_eq_u32 s83, 12
	s_cselect_b32 s71, s21, s51
	s_cselect_b32 s70, s20, s50
	s_cselect_b32 s51, s23, s19
	s_cselect_b32 s50, s22, s17
	v_lshl_add_u64 v[158:159], s[40:41], 0, v[136:137]
	s_add_i32 m0, s25, 0xc000
	ds_read_b128 v[190:193], v153
	ds_read_b128 v[194:197], v153 offset:1024
	ds_read_b128 v[198:201], v153 offset:2048
	ds_read_b128 v[202:205], v153 offset:3072
	ds_read_b128 v[206:209], v153 offset:4096
	ds_read_b128 v[210:213], v153 offset:5120
	ds_read_b128 v[214:217], v153 offset:6144
	ds_read_b128 v[218:221], v153 offset:7168
	global_load_lds_dwordx4 v[158:159], off
	v_lshl_add_u64 v[158:159], s[40:41], 0, v[138:139]
	s_add_i32 m0, s25, 0xe000
	s_nop 0
	global_load_lds_dwordx4 v[158:159], off
	s_waitcnt vmcnt(24)
	s_waitcnt lgkmcnt(0)
	s_barrier
	s_setprio 1
	s_waitcnt lgkmcnt(0)
	v_mfma_f32_16x16x32_bf16 v[124:127], v[144:147], v[190:193], v[124:127]
	v_mfma_f32_16x16x32_bf16 v[120:123], v[162:165], v[190:193], v[120:123]
	v_mfma_f32_16x16x32_bf16 v[116:119], v[144:147], v[198:201], v[116:119]
	v_mfma_f32_16x16x32_bf16 v[108:111], v[162:165], v[198:201], v[108:111]
	v_mfma_f32_16x16x32_bf16 v[100:103], v[144:147], v[206:209], v[100:103]
	v_mfma_f32_16x16x32_bf16 v[92:95], v[162:165], v[206:209], v[92:95]
	v_mfma_f32_16x16x32_bf16 v[84:87], v[144:147], v[214:217], v[84:87]
	v_mfma_f32_16x16x32_bf16 v[76:79], v[162:165], v[214:217], v[76:79]
	v_mfma_f32_16x16x32_bf16 v[124:127], v[154:157], v[194:197], v[124:127]
	v_mfma_f32_16x16x32_bf16 v[120:123], v[166:169], v[194:197], v[120:123]
	v_mfma_f32_16x16x32_bf16 v[116:119], v[154:157], v[202:205], v[116:119]
	v_mfma_f32_16x16x32_bf16 v[108:111], v[166:169], v[202:205], v[108:111]
	v_mfma_f32_16x16x32_bf16 v[100:103], v[154:157], v[210:213], v[100:103]
	v_mfma_f32_16x16x32_bf16 v[92:95], v[166:169], v[210:213], v[92:95]
	v_mfma_f32_16x16x32_bf16 v[84:87], v[154:157], v[218:221], v[84:87]
	v_mfma_f32_16x16x32_bf16 v[76:79], v[166:169], v[218:221], v[76:79]
	s_setprio 0
	s_setprio 1
	v_mfma_f32_16x16x32_bf16 v[112:115], v[170:173], v[190:193], v[112:115]
	v_mfma_f32_16x16x32_bf16 v[104:107], v[182:185], v[190:193], v[104:107]
	v_mfma_f32_16x16x32_bf16 v[96:99], v[170:173], v[198:201], v[96:99]
	v_mfma_f32_16x16x32_bf16 v[88:91], v[182:185], v[198:201], v[88:91]
	v_mfma_f32_16x16x32_bf16 v[80:83], v[170:173], v[206:209], v[80:83]
	v_mfma_f32_16x16x32_bf16 v[72:75], v[182:185], v[206:209], v[72:75]
	v_mfma_f32_16x16x32_bf16 v[68:71], v[170:173], v[214:217], v[68:71]
	v_mfma_f32_16x16x32_bf16 v[64:67], v[182:185], v[214:217], v[64:67]
	v_mfma_f32_16x16x32_bf16 v[112:115], v[174:177], v[194:197], v[112:115]
	v_mfma_f32_16x16x32_bf16 v[104:107], v[186:189], v[194:197], v[104:107]
	v_mfma_f32_16x16x32_bf16 v[96:99], v[174:177], v[202:205], v[96:99]
	v_mfma_f32_16x16x32_bf16 v[88:91], v[186:189], v[202:205], v[88:91]
	v_mfma_f32_16x16x32_bf16 v[80:83], v[174:177], v[210:213], v[80:83]
	v_mfma_f32_16x16x32_bf16 v[72:75], v[186:189], v[210:213], v[72:75]
	v_mfma_f32_16x16x32_bf16 v[68:71], v[174:177], v[218:221], v[68:71]
	v_mfma_f32_16x16x32_bf16 v[64:67], v[186:189], v[218:221], v[64:67]
	s_setprio 0
	s_barrier
	s_add_i32 s84, s79, s3
	v_lshl_add_u64 v[158:159], s[50:51], 0, v[132:133]
	s_mov_b32 m0, s84
	ds_read_b128 v[190:193], v153 offset:16384
	ds_read_b128 v[194:197], v153 offset:17408
	ds_read_b128 v[198:201], v153 offset:18432
	ds_read_b128 v[202:205], v153 offset:19456
	ds_read_b128 v[206:209], v153 offset:20480
	ds_read_b128 v[210:213], v153 offset:21504
	ds_read_b128 v[214:217], v153 offset:22528
	ds_read_b128 v[218:221], v153 offset:23552
	global_load_lds_dwordx4 v[158:159], off
	s_add_i32 m0, s84, 0x2000
	s_add_u32 s84, s50, 0x40000
	v_lshl_add_u64 v[178:179], s[50:51], 0, v[128:129]
	s_addc_u32 s85, s51, 0
	s_add_i32 s86, s80, s3
	global_load_lds_dwordx4 v[178:179], off
	v_lshl_add_u64 v[222:223], s[84:85], 0, v[132:133]
	s_mov_b32 m0, s86
	v_lshl_add_u64 v[224:225], s[70:71], 0, v[130:131]
	global_load_lds_dwordx4 v[222:223], off
	v_lshl_add_u64 v[222:223], s[84:85], 0, v[128:129]
	s_add_i32 m0, s86, 0x2000
	s_nop 0
	global_load_lds_dwordx4 v[222:223], off
	v_lshl_add_u64 v[222:223], s[70:71], 0, v[134:135]
	s_mov_b32 m0, s25
	s_nop 0
	global_load_lds_dwordx4 v[222:223], off
	s_mov_b32 m0, s72
	s_nop 0
	global_load_lds_dwordx4 v[224:225], off
	s_waitcnt vmcnt(24)
	s_waitcnt lgkmcnt(0)
	s_barrier
	s_setprio 1
	s_waitcnt lgkmcnt(0)
	v_mfma_f32_16x16x32_bf16 v[60:63], v[144:147], v[190:193], v[60:63]
	v_mfma_f32_16x16x32_bf16 v[56:59], v[162:165], v[190:193], v[56:59]
	v_mfma_f32_16x16x32_bf16 v[52:55], v[144:147], v[198:201], v[52:55]
	v_mfma_f32_16x16x32_bf16 v[44:47], v[162:165], v[198:201], v[44:47]
	v_mfma_f32_16x16x32_bf16 v[36:39], v[144:147], v[206:209], v[36:39]
	v_mfma_f32_16x16x32_bf16 v[28:31], v[162:165], v[206:209], v[28:31]
	v_mfma_f32_16x16x32_bf16 v[20:23], v[144:147], v[214:217], v[20:23]
	v_mfma_f32_16x16x32_bf16 v[12:15], v[162:165], v[214:217], v[12:15]
	v_mfma_f32_16x16x32_bf16 v[60:63], v[154:157], v[194:197], v[60:63]
	v_mfma_f32_16x16x32_bf16 v[56:59], v[166:169], v[194:197], v[56:59]
	v_mfma_f32_16x16x32_bf16 v[52:55], v[154:157], v[202:205], v[52:55]
	v_mfma_f32_16x16x32_bf16 v[44:47], v[166:169], v[202:205], v[44:47]
	v_mfma_f32_16x16x32_bf16 v[36:39], v[154:157], v[210:213], v[36:39]
	v_mfma_f32_16x16x32_bf16 v[28:31], v[166:169], v[210:213], v[28:31]
	v_mfma_f32_16x16x32_bf16 v[20:23], v[154:157], v[218:221], v[20:23]
	v_mfma_f32_16x16x32_bf16 v[12:15], v[166:169], v[218:221], v[12:15]
	s_setprio 0
	s_setprio 1
	v_mfma_f32_16x16x32_bf16 v[48:51], v[170:173], v[190:193], v[48:51]
	v_mfma_f32_16x16x32_bf16 v[40:43], v[182:185], v[190:193], v[40:43]
	v_mfma_f32_16x16x32_bf16 v[32:35], v[170:173], v[198:201], v[32:35]
	v_mfma_f32_16x16x32_bf16 v[24:27], v[182:185], v[198:201], v[24:27]
	v_mfma_f32_16x16x32_bf16 v[16:19], v[170:173], v[206:209], v[16:19]
	v_mfma_f32_16x16x32_bf16 v[8:11], v[182:185], v[206:209], v[8:11]
	v_mfma_f32_16x16x32_bf16 v[4:7], v[170:173], v[214:217], v[4:7]
	v_mfma_f32_16x16x32_bf16 v[0:3], v[182:185], v[214:217], v[0:3]
	v_mfma_f32_16x16x32_bf16 v[48:51], v[174:177], v[194:197], v[48:51]
	v_mfma_f32_16x16x32_bf16 v[40:43], v[186:189], v[194:197], v[40:43]
	v_mfma_f32_16x16x32_bf16 v[32:35], v[174:177], v[202:205], v[32:35]
	v_mfma_f32_16x16x32_bf16 v[24:27], v[186:189], v[202:205], v[24:27]
	v_mfma_f32_16x16x32_bf16 v[16:19], v[174:177], v[210:213], v[16:19]
	v_mfma_f32_16x16x32_bf16 v[8:11], v[186:189], v[210:213], v[8:11]
	v_mfma_f32_16x16x32_bf16 v[4:7], v[174:177], v[218:221], v[4:7]
	v_mfma_f32_16x16x32_bf16 v[0:3], v[186:189], v[218:221], v[0:3]
	s_setprio 0
	s_barrier
	s_add_i32 s84, 0, 0x18000
	v_add_u32_e32 v160, s84, v149
	s_add_i32 s85, 0, 0x1c000
	ds_read_b128 v[144:147], v160
	ds_read_b128 v[154:157], v160 offset:1024
	ds_read_b128 v[162:165], v160 offset:2048
	ds_read_b128 v[166:169], v160 offset:3072
	v_add_u32_e32 v160, s85, v149
	ds_read_b128 v[170:173], v160
	ds_read_b128 v[174:177], v160 offset:1024
	ds_read_b128 v[182:185], v160 offset:2048
	ds_read_b128 v[186:189], v160 offset:3072
	s_add_u32 s70, s70, 0x40000
	s_addc_u32 s71, s71, 0
	s_mov_b32 m0, s73
	v_lshl_add_u64 v[226:227], s[70:71], 0, v[134:135]
	ds_read_b128 v[190:193], v153 offset:32768
	ds_read_b128 v[194:197], v153 offset:33792
	ds_read_b128 v[198:201], v153 offset:34816
	ds_read_b128 v[202:205], v153 offset:35840
	ds_read_b128 v[206:209], v153 offset:36864
	ds_read_b128 v[210:213], v153 offset:37888
	ds_read_b128 v[214:217], v153 offset:38912
	ds_read_b128 v[218:221], v153 offset:39936
	global_load_lds_dwordx4 v[226:227], off
	v_lshl_add_u64 v[226:227], s[70:71], 0, v[130:131]
	s_mov_b32 m0, s74
	s_nop 0
	global_load_lds_dwordx4 v[226:227], off
	s_waitcnt vmcnt(8)
	s_waitcnt lgkmcnt(0)
	s_barrier
	s_setprio 1
	s_waitcnt lgkmcnt(0)
	v_mfma_f32_16x16x32_bf16 v[124:127], v[144:147], v[190:193], v[124:127]
	v_mfma_f32_16x16x32_bf16 v[120:123], v[162:165], v[190:193], v[120:123]
	v_mfma_f32_16x16x32_bf16 v[116:119], v[144:147], v[198:201], v[116:119]
	v_mfma_f32_16x16x32_bf16 v[108:111], v[162:165], v[198:201], v[108:111]
	v_mfma_f32_16x16x32_bf16 v[100:103], v[144:147], v[206:209], v[100:103]
	v_mfma_f32_16x16x32_bf16 v[92:95], v[162:165], v[206:209], v[92:95]
	v_mfma_f32_16x16x32_bf16 v[84:87], v[144:147], v[214:217], v[84:87]
	v_mfma_f32_16x16x32_bf16 v[76:79], v[162:165], v[214:217], v[76:79]
	v_mfma_f32_16x16x32_bf16 v[124:127], v[154:157], v[194:197], v[124:127]
	v_mfma_f32_16x16x32_bf16 v[120:123], v[166:169], v[194:197], v[120:123]
	v_mfma_f32_16x16x32_bf16 v[116:119], v[154:157], v[202:205], v[116:119]
	v_mfma_f32_16x16x32_bf16 v[108:111], v[166:169], v[202:205], v[108:111]
	v_mfma_f32_16x16x32_bf16 v[100:103], v[154:157], v[210:213], v[100:103]
	v_mfma_f32_16x16x32_bf16 v[92:95], v[166:169], v[210:213], v[92:95]
	v_mfma_f32_16x16x32_bf16 v[84:87], v[154:157], v[218:221], v[84:87]
	v_mfma_f32_16x16x32_bf16 v[76:79], v[166:169], v[218:221], v[76:79]
	s_setprio 0
	s_setprio 1
	v_mfma_f32_16x16x32_bf16 v[112:115], v[170:173], v[190:193], v[112:115]
	v_mfma_f32_16x16x32_bf16 v[104:107], v[182:185], v[190:193], v[104:107]
	v_mfma_f32_16x16x32_bf16 v[96:99], v[170:173], v[198:201], v[96:99]
	v_mfma_f32_16x16x32_bf16 v[88:91], v[182:185], v[198:201], v[88:91]
	v_mfma_f32_16x16x32_bf16 v[80:83], v[170:173], v[206:209], v[80:83]
	v_mfma_f32_16x16x32_bf16 v[72:75], v[182:185], v[206:209], v[72:75]
	v_mfma_f32_16x16x32_bf16 v[68:71], v[170:173], v[214:217], v[68:71]
	v_mfma_f32_16x16x32_bf16 v[64:67], v[182:185], v[214:217], v[64:67]
	v_mfma_f32_16x16x32_bf16 v[112:115], v[174:177], v[194:197], v[112:115]
	v_mfma_f32_16x16x32_bf16 v[104:107], v[186:189], v[194:197], v[104:107]
	v_mfma_f32_16x16x32_bf16 v[96:99], v[174:177], v[202:205], v[96:99]
	v_mfma_f32_16x16x32_bf16 v[88:91], v[186:189], v[202:205], v[88:91]
	v_mfma_f32_16x16x32_bf16 v[80:83], v[174:177], v[210:213], v[80:83]
	v_mfma_f32_16x16x32_bf16 v[72:75], v[186:189], v[210:213], v[72:75]
	v_mfma_f32_16x16x32_bf16 v[68:71], v[174:177], v[218:221], v[68:71]
	v_mfma_f32_16x16x32_bf16 v[64:67], v[186:189], v[218:221], v[64:67]
	s_setprio 0
	s_barrier
	s_add_i32 s70, s84, s3
	v_lshl_add_u64 v[158:159], v[158:159], 0, s[8:9]
	s_mov_b32 m0, s70
	ds_read_b128 v[190:193], v153 offset:49152
	ds_read_b128 v[194:197], v153 offset:50176
	ds_read_b128 v[198:201], v153 offset:51200
	ds_read_b128 v[202:205], v153 offset:52224
	ds_read_b128 v[206:209], v153 offset:53248
	ds_read_b128 v[210:213], v153 offset:54272
	ds_read_b128 v[214:217], v153 offset:55296
	ds_read_b128 v[218:221], v153 offset:56320
	global_load_lds_dwordx4 v[158:159], off
	s_add_i32 m0, s70, 0x2000
	s_add_u32 s50, s50, 0x40080
	v_lshl_add_u64 v[158:159], v[178:179], 0, s[8:9]
	s_addc_u32 s51, s51, 0
	s_add_i32 s70, s85, s3
	global_load_lds_dwordx4 v[158:159], off
	v_lshl_add_u64 v[158:159], s[50:51], 0, v[132:133]
	s_mov_b32 m0, s70
	s_nop 0
	global_load_lds_dwordx4 v[158:159], off
	v_lshl_add_u64 v[158:159], s[50:51], 0, v[128:129]
	s_add_i32 m0, s70, 0x2000
	s_nop 0
	global_load_lds_dwordx4 v[158:159], off
	v_lshl_add_u64 v[158:159], v[222:223], 0, s[8:9]
	s_mov_b32 m0, s76
	s_nop 0
	global_load_lds_dwordx4 v[158:159], off
	v_lshl_add_u64 v[158:159], v[224:225], 0, s[8:9]
	s_mov_b32 m0, s77
	s_nop 0
	global_load_lds_dwordx4 v[158:159], off
	s_waitcnt vmcnt(8)
	s_waitcnt lgkmcnt(0)
	s_barrier
	s_setprio 1
	s_waitcnt lgkmcnt(0)
	v_mfma_f32_16x16x32_bf16 v[60:63], v[144:147], v[190:193], v[60:63]
	v_mfma_f32_16x16x32_bf16 v[56:59], v[162:165], v[190:193], v[56:59]
	v_mfma_f32_16x16x32_bf16 v[52:55], v[144:147], v[198:201], v[52:55]
	v_mfma_f32_16x16x32_bf16 v[44:47], v[162:165], v[198:201], v[44:47]
	v_mfma_f32_16x16x32_bf16 v[36:39], v[144:147], v[206:209], v[36:39]
	v_mfma_f32_16x16x32_bf16 v[28:31], v[162:165], v[206:209], v[28:31]
	v_mfma_f32_16x16x32_bf16 v[20:23], v[144:147], v[214:217], v[20:23]
	v_mfma_f32_16x16x32_bf16 v[12:15], v[162:165], v[214:217], v[12:15]
	v_mfma_f32_16x16x32_bf16 v[60:63], v[154:157], v[194:197], v[60:63]
	v_mfma_f32_16x16x32_bf16 v[56:59], v[166:169], v[194:197], v[56:59]
	v_mfma_f32_16x16x32_bf16 v[52:55], v[154:157], v[202:205], v[52:55]
	v_mfma_f32_16x16x32_bf16 v[44:47], v[166:169], v[202:205], v[44:47]
	v_mfma_f32_16x16x32_bf16 v[36:39], v[154:157], v[210:213], v[36:39]
	v_mfma_f32_16x16x32_bf16 v[28:31], v[166:169], v[210:213], v[28:31]
	v_mfma_f32_16x16x32_bf16 v[20:23], v[154:157], v[218:221], v[20:23]
	v_mfma_f32_16x16x32_bf16 v[12:15], v[166:169], v[218:221], v[12:15]
	s_setprio 0
	s_setprio 1
	v_mfma_f32_16x16x32_bf16 v[48:51], v[170:173], v[190:193], v[48:51]
	v_mfma_f32_16x16x32_bf16 v[40:43], v[182:185], v[190:193], v[40:43]
	v_mfma_f32_16x16x32_bf16 v[32:35], v[170:173], v[198:201], v[32:35]
	v_mfma_f32_16x16x32_bf16 v[24:27], v[182:185], v[198:201], v[24:27]
	v_mfma_f32_16x16x32_bf16 v[16:19], v[170:173], v[206:209], v[16:19]
	v_mfma_f32_16x16x32_bf16 v[8:11], v[182:185], v[206:209], v[8:11]
	v_mfma_f32_16x16x32_bf16 v[4:7], v[170:173], v[214:217], v[4:7]
	v_mfma_f32_16x16x32_bf16 v[0:3], v[182:185], v[214:217], v[0:3]
	v_mfma_f32_16x16x32_bf16 v[48:51], v[174:177], v[194:197], v[48:51]
	v_mfma_f32_16x16x32_bf16 v[40:43], v[186:189], v[194:197], v[40:43]
	v_mfma_f32_16x16x32_bf16 v[32:35], v[174:177], v[202:205], v[32:35]
	v_mfma_f32_16x16x32_bf16 v[24:27], v[186:189], v[202:205], v[24:27]
	v_mfma_f32_16x16x32_bf16 v[16:19], v[174:177], v[210:213], v[16:19]
	v_mfma_f32_16x16x32_bf16 v[8:11], v[186:189], v[210:213], v[8:11]
	v_mfma_f32_16x16x32_bf16 v[4:7], v[174:177], v[218:221], v[4:7]
	v_mfma_f32_16x16x32_bf16 v[0:3], v[186:189], v[218:221], v[0:3]
	s_setprio 0
	s_barrier
	s_add_i32 s83, s83, 2
	s_add_u32 s40, s40, 0x100
	s_addc_u32 s41, s41, 0
	s_add_u32 s17, s17, 0x100
	s_addc_u32 s19, s19, 0
	s_cmp_gt_u32 s83, 13

.LBB0_546:
	s_add_u32 s10, s10, 0x40080
	s_addc_u32 s11, s11, 0
	s_add_u32 s1, s12, 0x100
	v_mov_b32_e32 v0, 0
	s_addc_u32 s9, s13, 0
	s_mov_b32 s25, -2
	v_mov_b32_e32 v1, v0
	v_mov_b32_e32 v2, v0
	v_mov_b32_e32 v3, v0
	v_mov_b32_e32 v4, v0
	v_mov_b32_e32 v5, v0
	v_mov_b32_e32 v6, v0
	v_mov_b32_e32 v7, v0
	v_mov_b32_e32 v16, v0
	v_mov_b32_e32 v17, v0
	v_mov_b32_e32 v18, v0
	v_mov_b32_e32 v19, v0
	v_mov_b32_e32 v20, v0
	v_mov_b32_e32 v21, v0
	v_mov_b32_e32 v22, v0
	v_mov_b32_e32 v23, v0
	v_mov_b32_e32 v32, v0
	v_mov_b32_e32 v33, v0
	v_mov_b32_e32 v34, v0
	v_mov_b32_e32 v35, v0
	v_mov_b32_e32 v36, v0
	v_mov_b32_e32 v37, v0
	v_mov_b32_e32 v38, v0
	v_mov_b32_e32 v39, v0
	v_mov_b32_e32 v48, v0
	v_mov_b32_e32 v49, v0
	v_mov_b32_e32 v50, v0
	v_mov_b32_e32 v51, v0
	v_mov_b32_e32 v52, v0
	v_mov_b32_e32 v53, v0
	v_mov_b32_e32 v54, v0
	v_mov_b32_e32 v55, v0
	v_mov_b32_e32 v8, v0
	v_mov_b32_e32 v9, v0
	v_mov_b32_e32 v10, v0
	v_mov_b32_e32 v11, v0
	v_mov_b32_e32 v12, v0
	v_mov_b32_e32 v13, v0
	v_mov_b32_e32 v14, v0
	v_mov_b32_e32 v15, v0
	v_mov_b32_e32 v24, v0
	v_mov_b32_e32 v25, v0
	v_mov_b32_e32 v26, v0
	v_mov_b32_e32 v27, v0
	v_mov_b32_e32 v28, v0
	v_mov_b32_e32 v29, v0
	v_mov_b32_e32 v30, v0
	v_mov_b32_e32 v31, v0
	v_mov_b32_e32 v40, v0
	v_mov_b32_e32 v41, v0
	v_mov_b32_e32 v42, v0
	v_mov_b32_e32 v43, v0
	v_mov_b32_e32 v44, v0
	v_mov_b32_e32 v45, v0
	v_mov_b32_e32 v46, v0
	v_mov_b32_e32 v47, v0
	v_mov_b32_e32 v56, v0
	v_mov_b32_e32 v57, v0
	v_mov_b32_e32 v58, v0
	v_mov_b32_e32 v59, v0
	v_mov_b32_e32 v60, v0
	v_mov_b32_e32 v61, v0
	v_mov_b32_e32 v62, v0
	v_mov_b32_e32 v63, v0
	v_mov_b32_e32 v64, v0
	v_mov_b32_e32 v65, v0
	v_mov_b32_e32 v66, v0
	v_mov_b32_e32 v67, v0
	v_mov_b32_e32 v68, v0
	v_mov_b32_e32 v69, v0
	v_mov_b32_e32 v70, v0
	v_mov_b32_e32 v71, v0
	v_mov_b32_e32 v80, v0
	v_mov_b32_e32 v81, v0
	v_mov_b32_e32 v82, v0
	v_mov_b32_e32 v83, v0
	v_mov_b32_e32 v84, v0
	v_mov_b32_e32 v85, v0
	v_mov_b32_e32 v86, v0
	v_mov_b32_e32 v87, v0
	v_mov_b32_e32 v96, v0
	v_mov_b32_e32 v97, v0
	v_mov_b32_e32 v98, v0
	v_mov_b32_e32 v99, v0
	v_mov_b32_e32 v100, v0
	v_mov_b32_e32 v101, v0
	v_mov_b32_e32 v102, v0
	v_mov_b32_e32 v103, v0
	v_mov_b32_e32 v112, v0
	v_mov_b32_e32 v113, v0
	v_mov_b32_e32 v114, v0
	v_mov_b32_e32 v115, v0
	v_mov_b32_e32 v116, v0
	v_mov_b32_e32 v117, v0
	v_mov_b32_e32 v118, v0
	v_mov_b32_e32 v119, v0
	v_mov_b32_e32 v72, v0
	v_mov_b32_e32 v73, v0
	v_mov_b32_e32 v74, v0
	v_mov_b32_e32 v75, v0
	v_mov_b32_e32 v76, v0
	v_mov_b32_e32 v77, v0
	v_mov_b32_e32 v78, v0
	v_mov_b32_e32 v79, v0
	v_mov_b32_e32 v88, v0
	v_mov_b32_e32 v89, v0
	v_mov_b32_e32 v90, v0
	v_mov_b32_e32 v91, v0
	v_mov_b32_e32 v92, v0
	v_mov_b32_e32 v93, v0
	v_mov_b32_e32 v94, v0
	v_mov_b32_e32 v95, v0
	v_mov_b32_e32 v104, v0
	v_mov_b32_e32 v105, v0
	v_mov_b32_e32 v106, v0
	v_mov_b32_e32 v107, v0
	v_mov_b32_e32 v108, v0
	v_mov_b32_e32 v109, v0
	v_mov_b32_e32 v110, v0
	v_mov_b32_e32 v111, v0
	v_mov_b32_e32 v124, v0
	v_mov_b32_e32 v125, v0
	v_mov_b32_e32 v126, v0
	v_mov_b32_e32 v127, v0
	v_mov_b32_e32 v120, v0
	v_mov_b32_e32 v121, v0
	v_mov_b32_e32 v122, v0
	v_mov_b32_e32 v123, v0
	s_cmp_eq_u32 s52, 1
	s_cbranch_scc1 .LBB0_547
	ds_read_b128 v[154:157], v149
	ds_read_b128 v[158:161], v149 offset:1024
	ds_read_b128 v[162:165], v149 offset:2048
	ds_read_b128 v[166:169], v149 offset:3072
	ds_read_b128 v[170:173], v150
	ds_read_b128 v[174:177], v150 offset:1024
	ds_read_b128 v[182:185], v150 offset:2048
	ds_read_b128 v[186:189], v150 offset:3072
	s_add_u32 s12, s10, 0xfffc0080
	s_addc_u32 s13, s11, -1
	s_cmp_eq_u32 s25, 12
	s_cselect_b32 s45, s37, s13
	s_cselect_b32 s44, s36, s12
	s_cselect_b32 s13, s43, s9
	s_cselect_b32 s12, s42, s1
	v_lshl_add_u64 v[144:145], s[10:11], 0, v[136:137]
	s_add_i32 m0, s48, 0xc000
	ds_read_b128 v[190:193], v151
	ds_read_b128 v[194:197], v151 offset:1024
	ds_read_b128 v[198:201], v151 offset:2048
	ds_read_b128 v[202:205], v151 offset:3072
	ds_read_b128 v[206:209], v151 offset:4096
	ds_read_b128 v[210:213], v151 offset:5120
	ds_read_b128 v[214:217], v151 offset:6144
	ds_read_b128 v[218:221], v151 offset:7168
	global_load_lds_dwordx4 v[144:145], off
	v_lshl_add_u64 v[144:145], s[10:11], 0, v[138:139]
	s_add_i32 m0, s48, 0xe000
	s_nop 0
	global_load_lds_dwordx4 v[144:145], off
	s_waitcnt vmcnt(24)
	s_waitcnt lgkmcnt(0)
	s_barrier
	s_setprio 1
	s_waitcnt lgkmcnt(0)
	v_mfma_f32_16x16x32_bf16 v[120:123], v[154:157], v[190:193], v[120:123]
	v_mfma_f32_16x16x32_bf16 v[124:127], v[162:165], v[190:193], v[124:127]
	v_mfma_f32_16x16x32_bf16 v[108:111], v[154:157], v[198:201], v[108:111]
	v_mfma_f32_16x16x32_bf16 v[104:107], v[162:165], v[198:201], v[104:107]
	v_mfma_f32_16x16x32_bf16 v[92:95], v[154:157], v[206:209], v[92:95]
	v_mfma_f32_16x16x32_bf16 v[88:91], v[162:165], v[206:209], v[88:91]
	v_mfma_f32_16x16x32_bf16 v[76:79], v[154:157], v[214:217], v[76:79]
	v_mfma_f32_16x16x32_bf16 v[72:75], v[162:165], v[214:217], v[72:75]
	v_mfma_f32_16x16x32_bf16 v[120:123], v[158:161], v[194:197], v[120:123]
	v_mfma_f32_16x16x32_bf16 v[124:127], v[166:169], v[194:197], v[124:127]
	v_mfma_f32_16x16x32_bf16 v[108:111], v[158:161], v[202:205], v[108:111]
	v_mfma_f32_16x16x32_bf16 v[104:107], v[166:169], v[202:205], v[104:107]
	v_mfma_f32_16x16x32_bf16 v[92:95], v[158:161], v[210:213], v[92:95]
	v_mfma_f32_16x16x32_bf16 v[88:91], v[166:169], v[210:213], v[88:91]
	v_mfma_f32_16x16x32_bf16 v[76:79], v[158:161], v[218:221], v[76:79]
	v_mfma_f32_16x16x32_bf16 v[72:75], v[166:169], v[218:221], v[72:75]
	s_setprio 0
	s_setprio 1
	v_mfma_f32_16x16x32_bf16 v[116:119], v[170:173], v[190:193], v[116:119]
	v_mfma_f32_16x16x32_bf16 v[112:115], v[182:185], v[190:193], v[112:115]
	v_mfma_f32_16x16x32_bf16 v[100:103], v[170:173], v[198:201], v[100:103]
	v_mfma_f32_16x16x32_bf16 v[96:99], v[182:185], v[198:201], v[96:99]
	v_mfma_f32_16x16x32_bf16 v[84:87], v[170:173], v[206:209], v[84:87]
	v_mfma_f32_16x16x32_bf16 v[80:83], v[182:185], v[206:209], v[80:83]
	v_mfma_f32_16x16x32_bf16 v[68:71], v[170:173], v[214:217], v[68:71]
	v_mfma_f32_16x16x32_bf16 v[64:67], v[182:185], v[214:217], v[64:67]
	v_mfma_f32_16x16x32_bf16 v[116:119], v[174:177], v[194:197], v[116:119]
	v_mfma_f32_16x16x32_bf16 v[112:115], v[186:189], v[194:197], v[112:115]
	v_mfma_f32_16x16x32_bf16 v[100:103], v[174:177], v[202:205], v[100:103]
	v_mfma_f32_16x16x32_bf16 v[96:99], v[186:189], v[202:205], v[96:99]
	v_mfma_f32_16x16x32_bf16 v[84:87], v[174:177], v[210:213], v[84:87]
	v_mfma_f32_16x16x32_bf16 v[80:83], v[186:189], v[210:213], v[80:83]
	v_mfma_f32_16x16x32_bf16 v[68:71], v[174:177], v[218:221], v[68:71]
	v_mfma_f32_16x16x32_bf16 v[64:67], v[186:189], v[218:221], v[64:67]
	s_setprio 0
	s_barrier
	s_add_i32 s26, s56, s46
	v_lshl_add_u64 v[144:145], s[12:13], 0, v[132:133]
	s_mov_b32 m0, s26
	ds_read_b128 v[190:193], v151 offset:16384
	ds_read_b128 v[194:197], v151 offset:17408
	ds_read_b128 v[198:201], v151 offset:18432
	ds_read_b128 v[202:205], v151 offset:19456
	ds_read_b128 v[206:209], v151 offset:20480
	ds_read_b128 v[210:213], v151 offset:21504
	ds_read_b128 v[214:217], v151 offset:22528
	ds_read_b128 v[218:221], v151 offset:23552
	global_load_lds_dwordx4 v[144:145], off
	s_add_i32 m0, s26, 0x2000
	s_add_u32 s26, s12, 0x40000
	v_lshl_add_u64 v[178:179], s[12:13], 0, v[128:129]
	s_addc_u32 s27, s13, 0
	s_add_i32 s29, s57, s46
	global_load_lds_dwordx4 v[178:179], off
	v_lshl_add_u64 v[180:181], s[26:27], 0, v[132:133]
	s_mov_b32 m0, s29
	v_lshl_add_u64 v[222:223], s[44:45], 0, v[130:131]
	global_load_lds_dwordx4 v[180:181], off
	v_lshl_add_u64 v[180:181], s[26:27], 0, v[128:129]
	s_add_i32 m0, s29, 0x2000
	s_nop 0
	global_load_lds_dwordx4 v[180:181], off
	v_lshl_add_u64 v[180:181], s[44:45], 0, v[134:135]
	s_mov_b32 m0, s48
	s_nop 0
	global_load_lds_dwordx4 v[180:181], off
	s_mov_b32 m0, s49
	s_nop 0
	global_load_lds_dwordx4 v[222:223], off
	s_waitcnt vmcnt(24)
	s_waitcnt lgkmcnt(0)
	s_barrier
	s_setprio 1
	s_waitcnt lgkmcnt(0)
	v_mfma_f32_16x16x32_bf16 v[60:63], v[154:157], v[190:193], v[60:63]
	v_mfma_f32_16x16x32_bf16 v[56:59], v[162:165], v[190:193], v[56:59]
	v_mfma_f32_16x16x32_bf16 v[44:47], v[154:157], v[198:201], v[44:47]
	v_mfma_f32_16x16x32_bf16 v[40:43], v[162:165], v[198:201], v[40:43]
	v_mfma_f32_16x16x32_bf16 v[28:31], v[154:157], v[206:209], v[28:31]
	v_mfma_f32_16x16x32_bf16 v[24:27], v[162:165], v[206:209], v[24:27]
	v_mfma_f32_16x16x32_bf16 v[12:15], v[154:157], v[214:217], v[12:15]
	v_mfma_f32_16x16x32_bf16 v[8:11], v[162:165], v[214:217], v[8:11]
	v_mfma_f32_16x16x32_bf16 v[60:63], v[158:161], v[194:197], v[60:63]
	v_mfma_f32_16x16x32_bf16 v[56:59], v[166:169], v[194:197], v[56:59]
	v_mfma_f32_16x16x32_bf16 v[44:47], v[158:161], v[202:205], v[44:47]
	v_mfma_f32_16x16x32_bf16 v[40:43], v[166:169], v[202:205], v[40:43]
	v_mfma_f32_16x16x32_bf16 v[28:31], v[158:161], v[210:213], v[28:31]
	v_mfma_f32_16x16x32_bf16 v[24:27], v[166:169], v[210:213], v[24:27]
	v_mfma_f32_16x16x32_bf16 v[12:15], v[158:161], v[218:221], v[12:15]
	v_mfma_f32_16x16x32_bf16 v[8:11], v[166:169], v[218:221], v[8:11]
	s_setprio 0
	s_setprio 1
	v_mfma_f32_16x16x32_bf16 v[52:55], v[170:173], v[190:193], v[52:55]
	v_mfma_f32_16x16x32_bf16 v[48:51], v[182:185], v[190:193], v[48:51]
	v_mfma_f32_16x16x32_bf16 v[36:39], v[170:173], v[198:201], v[36:39]
	v_mfma_f32_16x16x32_bf16 v[32:35], v[182:185], v[198:201], v[32:35]
	v_mfma_f32_16x16x32_bf16 v[20:23], v[170:173], v[206:209], v[20:23]
	v_mfma_f32_16x16x32_bf16 v[16:19], v[182:185], v[206:209], v[16:19]
	v_mfma_f32_16x16x32_bf16 v[4:7], v[170:173], v[214:217], v[4:7]
	v_mfma_f32_16x16x32_bf16 v[0:3], v[182:185], v[214:217], v[0:3]
	v_mfma_f32_16x16x32_bf16 v[52:55], v[174:177], v[194:197], v[52:55]
	v_mfma_f32_16x16x32_bf16 v[48:51], v[186:189], v[194:197], v[48:51]
	v_mfma_f32_16x16x32_bf16 v[36:39], v[174:177], v[202:205], v[36:39]
	v_mfma_f32_16x16x32_bf16 v[32:35], v[186:189], v[202:205], v[32:35]
	v_mfma_f32_16x16x32_bf16 v[20:23], v[174:177], v[210:213], v[20:23]
	v_mfma_f32_16x16x32_bf16 v[16:19], v[186:189], v[210:213], v[16:19]
	v_mfma_f32_16x16x32_bf16 v[4:7], v[174:177], v[218:221], v[4:7]
	v_mfma_f32_16x16x32_bf16 v[0:3], v[186:189], v[218:221], v[0:3]
	s_setprio 0
	s_barrier
	s_add_i32 s29, 0, 0x18000
	v_add_u32_e32 v153, s29, v147
	s_add_i32 s60, 0, 0x1c000
	ds_read_b128 v[154:157], v153
	ds_read_b128 v[158:161], v153 offset:1024
	ds_read_b128 v[162:165], v153 offset:2048
	ds_read_b128 v[166:169], v153 offset:3072
	v_add_u32_e32 v153, s60, v147
	ds_read_b128 v[170:173], v153
	ds_read_b128 v[174:177], v153 offset:1024
	ds_read_b128 v[182:185], v153 offset:2048
	ds_read_b128 v[186:189], v153 offset:3072
	s_add_u32 s26, s44, 0x40000
	s_addc_u32 s27, s45, 0
	s_mov_b32 m0, s50
	v_lshl_add_u64 v[224:225], s[26:27], 0, v[134:135]
	ds_read_b128 v[190:193], v151 offset:32768
	ds_read_b128 v[194:197], v151 offset:33792
	ds_read_b128 v[198:201], v151 offset:34816
	ds_read_b128 v[202:205], v151 offset:35840
	ds_read_b128 v[206:209], v151 offset:36864
	ds_read_b128 v[210:213], v151 offset:37888
	ds_read_b128 v[214:217], v151 offset:38912
	ds_read_b128 v[218:221], v151 offset:39936
	global_load_lds_dwordx4 v[224:225], off
	v_lshl_add_u64 v[224:225], s[26:27], 0, v[130:131]
	s_mov_b32 m0, s51
	s_nop 0
	global_load_lds_dwordx4 v[224:225], off
	s_waitcnt vmcnt(8)
	s_waitcnt lgkmcnt(0)
	s_barrier
	s_setprio 1
	s_waitcnt lgkmcnt(0)
	v_mfma_f32_16x16x32_bf16 v[120:123], v[154:157], v[190:193], v[120:123]
	v_mfma_f32_16x16x32_bf16 v[124:127], v[162:165], v[190:193], v[124:127]
	v_mfma_f32_16x16x32_bf16 v[108:111], v[154:157], v[198:201], v[108:111]
	v_mfma_f32_16x16x32_bf16 v[104:107], v[162:165], v[198:201], v[104:107]
	v_mfma_f32_16x16x32_bf16 v[92:95], v[154:157], v[206:209], v[92:95]
	v_mfma_f32_16x16x32_bf16 v[88:91], v[162:165], v[206:209], v[88:91]
	v_mfma_f32_16x16x32_bf16 v[76:79], v[154:157], v[214:217], v[76:79]
	v_mfma_f32_16x16x32_bf16 v[72:75], v[162:165], v[214:217], v[72:75]
	v_mfma_f32_16x16x32_bf16 v[120:123], v[158:161], v[194:197], v[120:123]
	v_mfma_f32_16x16x32_bf16 v[124:127], v[166:169], v[194:197], v[124:127]
	v_mfma_f32_16x16x32_bf16 v[108:111], v[158:161], v[202:205], v[108:111]
	v_mfma_f32_16x16x32_bf16 v[104:107], v[166:169], v[202:205], v[104:107]
	v_mfma_f32_16x16x32_bf16 v[92:95], v[158:161], v[210:213], v[92:95]
	v_mfma_f32_16x16x32_bf16 v[88:91], v[166:169], v[210:213], v[88:91]
	v_mfma_f32_16x16x32_bf16 v[76:79], v[158:161], v[218:221], v[76:79]
	v_mfma_f32_16x16x32_bf16 v[72:75], v[166:169], v[218:221], v[72:75]
	s_setprio 0
	s_setprio 1
	v_mfma_f32_16x16x32_bf16 v[116:119], v[170:173], v[190:193], v[116:119]
	v_mfma_f32_16x16x32_bf16 v[112:115], v[182:185], v[190:193], v[112:115]
	v_mfma_f32_16x16x32_bf16 v[100:103], v[170:173], v[198:201], v[100:103]
	v_mfma_f32_16x16x32_bf16 v[96:99], v[182:185], v[198:201], v[96:99]
	v_mfma_f32_16x16x32_bf16 v[84:87], v[170:173], v[206:209], v[84:87]
	v_mfma_f32_16x16x32_bf16 v[80:83], v[182:185], v[206:209], v[80:83]
	v_mfma_f32_16x16x32_bf16 v[68:71], v[170:173], v[214:217], v[68:71]
	v_mfma_f32_16x16x32_bf16 v[64:67], v[182:185], v[214:217], v[64:67]
	v_mfma_f32_16x16x32_bf16 v[116:119], v[174:177], v[194:197], v[116:119]
	v_mfma_f32_16x16x32_bf16 v[112:115], v[186:189], v[194:197], v[112:115]
	v_mfma_f32_16x16x32_bf16 v[100:103], v[174:177], v[202:205], v[100:103]
	v_mfma_f32_16x16x32_bf16 v[96:99], v[186:189], v[202:205], v[96:99]
	v_mfma_f32_16x16x32_bf16 v[84:87], v[174:177], v[210:213], v[84:87]
	v_mfma_f32_16x16x32_bf16 v[80:83], v[186:189], v[210:213], v[80:83]
	v_mfma_f32_16x16x32_bf16 v[68:71], v[174:177], v[218:221], v[68:71]
	v_mfma_f32_16x16x32_bf16 v[64:67], v[186:189], v[218:221], v[64:67]
	s_setprio 0
	s_barrier
	s_add_i32 s26, s29, s46
	v_lshl_add_u64 v[144:145], v[144:145], 0, s[16:17]
	s_mov_b32 m0, s26
	ds_read_b128 v[190:193], v151 offset:49152
	ds_read_b128 v[194:197], v151 offset:50176
	ds_read_b128 v[198:201], v151 offset:51200
	ds_read_b128 v[202:205], v151 offset:52224
	ds_read_b128 v[206:209], v151 offset:53248
	ds_read_b128 v[210:213], v151 offset:54272
	ds_read_b128 v[214:217], v151 offset:55296
	ds_read_b128 v[218:221], v151 offset:56320
	global_load_lds_dwordx4 v[144:145], off
	s_add_i32 m0, s26, 0x2000
	s_add_u32 s12, s12, 0x40080
	v_lshl_add_u64 v[144:145], v[178:179], 0, s[16:17]
	s_addc_u32 s13, s13, 0
	s_add_i32 s26, s60, s46
	global_load_lds_dwordx4 v[144:145], off
	v_lshl_add_u64 v[144:145], s[12:13], 0, v[132:133]
	s_mov_b32 m0, s26
	s_nop 0
	global_load_lds_dwordx4 v[144:145], off
	v_lshl_add_u64 v[144:145], s[12:13], 0, v[128:129]
	s_add_i32 m0, s26, 0x2000
	s_nop 0
	global_load_lds_dwordx4 v[144:145], off
	v_lshl_add_u64 v[144:145], v[180:181], 0, s[16:17]
	s_mov_b32 m0, s53
	s_nop 0
	global_load_lds_dwordx4 v[144:145], off
	v_lshl_add_u64 v[144:145], v[222:223], 0, s[16:17]
	s_mov_b32 m0, s54
	s_nop 0
	global_load_lds_dwordx4 v[144:145], off
	s_waitcnt vmcnt(8)
	s_waitcnt lgkmcnt(0)
	s_barrier
	s_setprio 1
	s_waitcnt lgkmcnt(0)
	v_mfma_f32_16x16x32_bf16 v[60:63], v[154:157], v[190:193], v[60:63]
	v_mfma_f32_16x16x32_bf16 v[56:59], v[162:165], v[190:193], v[56:59]
	v_mfma_f32_16x16x32_bf16 v[44:47], v[154:157], v[198:201], v[44:47]
	v_mfma_f32_16x16x32_bf16 v[40:43], v[162:165], v[198:201], v[40:43]
	v_mfma_f32_16x16x32_bf16 v[28:31], v[154:157], v[206:209], v[28:31]
	v_mfma_f32_16x16x32_bf16 v[24:27], v[162:165], v[206:209], v[24:27]
	v_mfma_f32_16x16x32_bf16 v[12:15], v[154:157], v[214:217], v[12:15]
	v_mfma_f32_16x16x32_bf16 v[8:11], v[162:165], v[214:217], v[8:11]
	v_mfma_f32_16x16x32_bf16 v[60:63], v[158:161], v[194:197], v[60:63]
	v_mfma_f32_16x16x32_bf16 v[56:59], v[166:169], v[194:197], v[56:59]
	v_mfma_f32_16x16x32_bf16 v[44:47], v[158:161], v[202:205], v[44:47]
	v_mfma_f32_16x16x32_bf16 v[40:43], v[166:169], v[202:205], v[40:43]
	v_mfma_f32_16x16x32_bf16 v[28:31], v[158:161], v[210:213], v[28:31]
	v_mfma_f32_16x16x32_bf16 v[24:27], v[166:169], v[210:213], v[24:27]
	v_mfma_f32_16x16x32_bf16 v[12:15], v[158:161], v[218:221], v[12:15]
	v_mfma_f32_16x16x32_bf16 v[8:11], v[166:169], v[218:221], v[8:11]
	s_setprio 0
	s_setprio 1
	v_mfma_f32_16x16x32_bf16 v[52:55], v[170:173], v[190:193], v[52:55]
	v_mfma_f32_16x16x32_bf16 v[48:51], v[182:185], v[190:193], v[48:51]
	v_mfma_f32_16x16x32_bf16 v[36:39], v[170:173], v[198:201], v[36:39]
	v_mfma_f32_16x16x32_bf16 v[32:35], v[182:185], v[198:201], v[32:35]
	v_mfma_f32_16x16x32_bf16 v[20:23], v[170:173], v[206:209], v[20:23]
	v_mfma_f32_16x16x32_bf16 v[16:19], v[182:185], v[206:209], v[16:19]
	v_mfma_f32_16x16x32_bf16 v[4:7], v[170:173], v[214:217], v[4:7]
	v_mfma_f32_16x16x32_bf16 v[0:3], v[182:185], v[214:217], v[0:3]
	v_mfma_f32_16x16x32_bf16 v[52:55], v[174:177], v[194:197], v[52:55]
	v_mfma_f32_16x16x32_bf16 v[48:51], v[186:189], v[194:197], v[48:51]
	v_mfma_f32_16x16x32_bf16 v[36:39], v[174:177], v[202:205], v[36:39]
	v_mfma_f32_16x16x32_bf16 v[32:35], v[186:189], v[202:205], v[32:35]
	v_mfma_f32_16x16x32_bf16 v[20:23], v[174:177], v[210:213], v[20:23]
	v_mfma_f32_16x16x32_bf16 v[16:19], v[186:189], v[210:213], v[16:19]
	v_mfma_f32_16x16x32_bf16 v[4:7], v[174:177], v[218:221], v[4:7]
	v_mfma_f32_16x16x32_bf16 v[0:3], v[186:189], v[218:221], v[0:3]
	s_setprio 0
	s_barrier
	s_add_i32 s25, s25, 2
	s_add_u32 s10, s10, 0x100
	s_addc_u32 s11, s11, 0
	s_add_u32 s1, s1, 0x100
	s_addc_u32 s9, s9, 0
	s_cmp_gt_u32 s25, 13
